# MLA V-transpose tile: 32 ds_read_u16 kept 14 deep behind counted lgkmcnt (was 16 serialized pairs)
# speedup vs baseline: 1.0144x; 1.0001x over previous
; #define LAS __attribute__((address_space(3)))
; __device__ __forceinline__ void mlapost_tile(ArgP a, int l, int tl, LAS unsigned char* lds, int tid, int wave, int lane, int pm) {
;     ...
;     for (int rowid = tid >> 1; rowid < 384; rowid += 256) { const int half = tid & 1; unsigned w[16];
; #pragma unroll
;         for (int j = 0; j < 16; ++j) { const unsigned lo = *(const LAS bf16_t*)(lds + (half * 32 + 2 * j) * MVT_STR + rowid * 2), hi = *(const LAS bf16_t*)(lds + (half * 32 + 2 * j + 1) * MVT_STR + rowid * 2); w[j] = lo | (hi << 16); }
;         bf16_t* dst = (bf16_t*)(a->ws + OFF_VMT) + ((size_t)(g.b * 6 + rowid / 64) * 64 + (rowid & 63)) * P + g.p0 + 32 * half;
; #pragma unroll
;         for (int j = 0; j < 4; ++j) { u32x4 o = {w[4 * j], w[4 * j + 1], w[4 * j + 2], w[4 * j + 3]}; *(u32x4*)(dst + 8 * j) = o; }
;     }
.LBB0_757:
	ds_read_u16 v66, v19
	ds_read_u16 v67, v19 offset:784
	ds_read_u16 v68, v19 offset:1568
	ds_read_u16 v69, v19 offset:2352
	ds_read_u16 v70, v19 offset:3136
	ds_read_u16 v71, v19 offset:3920
	ds_read_u16 v72, v19 offset:4704
	ds_read_u16 v73, v19 offset:5488
	ds_read_u16 v74, v19 offset:6272
	ds_read_u16 v75, v19 offset:7056
	ds_read_u16 v76, v19 offset:7840
	ds_read_u16 v77, v19 offset:8624
	ds_read_u16 v78, v19 offset:9408
	ds_read_u16 v79, v19 offset:10192
	s_waitcnt lgkmcnt(12)
	v_lshl_or_b32 v46, v67, 16, v66
	ds_read_u16 v80, v19 offset:10976
	ds_read_u16 v81, v19 offset:11760
	s_waitcnt lgkmcnt(12)
	v_lshl_or_b32 v47, v69, 16, v68
	ds_read_u16 v82, v19 offset:12544
	ds_read_u16 v83, v19 offset:13328
	s_waitcnt lgkmcnt(12)
	v_lshl_or_b32 v48, v71, 16, v70
	ds_read_u16 v84, v19 offset:14112
	ds_read_u16 v85, v19 offset:14896
	s_waitcnt lgkmcnt(12)
	v_lshl_or_b32 v49, v73, 16, v72
	ds_read_u16 v86, v19 offset:15680
	ds_read_u16 v87, v19 offset:16464
	s_waitcnt lgkmcnt(12)
	v_lshl_or_b32 v50, v75, 16, v74
	ds_read_u16 v88, v19 offset:17248
	ds_read_u16 v89, v19 offset:18032
	s_waitcnt lgkmcnt(12)
	v_lshl_or_b32 v51, v77, 16, v76
	ds_read_u16 v90, v19 offset:18816
	ds_read_u16 v91, v19 offset:19600
	s_waitcnt lgkmcnt(12)
	v_lshl_or_b32 v52, v79, 16, v78
	ds_read_u16 v92, v19 offset:20384
	ds_read_u16 v93, v19 offset:21168
	s_waitcnt lgkmcnt(12)
	v_lshl_or_b32 v53, v81, 16, v80
	ds_read_u16 v94, v19 offset:21952
	ds_read_u16 v95, v19 offset:22736
	s_waitcnt lgkmcnt(12)
	v_lshl_or_b32 v54, v83, 16, v82
	ds_read_u16 v96, v19 offset:23520
	ds_read_u16 v97, v19 offset:24304
	v_add_u32_e32 v19, 0x200, v19
	s_waitcnt lgkmcnt(12)
	v_lshl_or_b32 v55, v85, 16, v84
	s_waitcnt lgkmcnt(10)
	v_lshl_or_b32 v56, v87, 16, v86
	s_waitcnt lgkmcnt(8)
	v_lshl_or_b32 v57, v89, 16, v88
	s_waitcnt lgkmcnt(6)
	v_lshl_or_b32 v58, v91, 16, v90
	s_waitcnt lgkmcnt(4)
	v_lshl_or_b32 v59, v93, 16, v92
	s_waitcnt lgkmcnt(2)
	v_lshl_or_b32 v60, v95, 16, v94
	s_waitcnt lgkmcnt(0)
	v_lshl_or_b32 v61, v97, 16, v96
	v_ashrrev_i32_e32 v23, 31, v21
	v_lshrrev_b32_e32 v23, 26, v23
	v_add_u32_e32 v23, v21, v23
	v_ashrrev_i32_e32 v23, 6, v23
	v_add_u32_e32 v62, s13, v23
	v_ashrrev_i32_e32 v63, 31, v62
	v_lshlrev_b64 v[62:63], 6, v[62:63]
	v_or_b32_e32 v23, v62, v16
	v_mad_u64_u32 v[64:65], s[14:15], v23, s82, v[30:31]
	s_movk_i32 s14, 0x7f
	v_add_u32_e32 v23, 0x100, v21
	v_cmp_lt_i32_e32 vcc, s14, v21
	v_mad_i32_i24 v65, v63, s82, v65
	s_or_b64 s[2:3], vcc, s[2:3]
	v_mov_b32_e32 v21, v23
	global_store_dwordx4 v[64:65], v[46:49], off
	global_store_dwordx4 v[64:65], v[50:53], off offset:16
	global_store_dwordx4 v[64:65], v[54:57], off offset:32
	global_store_dwordx4 v[64:65], v[58:61], off offset:48
	s_andn2_b64 exec, exec, s[2:3]
	s_cbranch_execnz .LBB0_757
	s_branch .LBB0_750
